# split grid barriers (arrive-only + deferred wait on the top counter) at scan->phase5, out->rowpass, down->rowpass, phase5->out, phase10->proj; weight conversions moved into the arrive/wait gaps of ste
# speedup vs baseline: 1.0228x; 1.0166x over previous
.LBB0_21:
	v_readlane_b32 s6, v244, 1
	v_readlane_b32 s7, v244, 2
	s_cmp_lt_u32 s70, 11
	v_readlane_b32 s0, v244, 3
	s_mov_b32 s71, s6
	s_cselect_b64 s[6:7], -1, 0
	s_add_i32 s20, s70, -9
	v_readlane_b32 s1, v244, 4
	v_readlane_b32 s3, v244, 0
	s_cmp_gt_u32 s70, 10
	s_cselect_b64 s[22:23], -1, 0
	s_waitcnt lgkmcnt(0)
	s_load_dwordx2 s[24:25], s[0:1], 0xb8
	s_and_b64 s[18:19], s[22:23], exec
	s_cselect_b32 s18, s20, s70
	s_cmp_lt_u32 s70, 2
	s_cselect_b32 s19, s70, s18
	s_cmp_eq_u32 s70, 6
	s_cbranch_scc1 .Lhk_6
	s_cmp_eq_u32 s70, 11
	s_cbranch_scc0 .Lhk_no
	s_cmpk_eq_u32 s71, 0x200
	s_cbranch_scc0 .Lhk_no
	s_waitcnt lgkmcnt(0)
	s_branch .Lcv_s11
.Lhk_6:
	s_cmpk_eq_u32 s71, 0x200
	s_cbranch_scc0 .Lhk_no
	s_waitcnt lgkmcnt(0)
	s_branch .Lcv_s6a
.Lcvret_disp:
	s_mov_b64 s[54:55], exec
	v_readlane_b32 vcc_lo, v244, 7
	v_readlane_b32 vcc_hi, v244, 8
	v_readlane_b32 s56, v244, 48
	v_readlane_b32 s57, v244, 49
	s_nop 1
	s_and_b64 exec, exec, vcc
	s_cbranch_execz .Lswcv_x
	ds_read_b32 v245, v157
	ds_read_b32 v246, v157 offset:4
	s_waitcnt lgkmcnt(0)
	v_readfirstlane_b32 s62, v245
	v_readfirstlane_b32 s63, v246
	s_mul_i32 s62, s62, s63
	s_mov_b32 s63, 0
.Lswcv_l:
	global_load_dword v245, v1, s[56:57] sc1
	s_add_i32 s63, s63, 1
	s_waitcnt vmcnt(0)
	v_readfirstlane_b32 vcc_lo, v245
	s_cmp_ge_u32 vcc_lo, s62
	s_cbranch_scc1 .Lswcv_x
	s_bitcmp1_b32 s63, 16
	s_cbranch_scc0 .Lswcv_l
.Lswcv_x:
	s_mov_b64 exec, s[54:55]
	s_barrier

.LBB0_44:
	s_mov_b64 s[54:55], exec
	v_readlane_b32 vcc_lo, v244, 7
	v_readlane_b32 vcc_hi, v244, 8
	v_readlane_b32 s56, v244, 48
	v_readlane_b32 s57, v244, 49
	s_nop 1
	s_and_b64 exec, exec, vcc
	s_cbranch_execz .Lsw10a_x
	ds_read_b32 v188, v157
	ds_read_b32 v189, v157 offset:4
	s_waitcnt lgkmcnt(0)
	v_readfirstlane_b32 s62, v188
	v_readfirstlane_b32 s63, v189
	s_mul_i32 s62, s62, s63
	s_mov_b32 s63, 0
.Lsw10a_l:
	global_load_dword v188, v1, s[56:57] sc1
	s_add_i32 s63, s63, 1
	s_waitcnt vmcnt(0)
	v_readfirstlane_b32 vcc_lo, v188
	s_cmp_ge_u32 vcc_lo, s62
	s_cbranch_scc1 .Lsw10a_x
	s_bitcmp1_b32 s63, 16
	s_cbranch_scc0 .Lsw10a_l
.Lsw10a_x:
	s_mov_b64 exec, s[54:55]
	s_barrier
	s_add_i32 s7, s6, s7
	s_min_i32 s36, s7, 0x4000
	s_cmp_lt_i32 s6, s36
	s_cbranch_scc0 .LBB0_335
	s_load_dwordx2 s[34:35], s[0:1], 0x90
	s_load_dwordx2 s[28:29], s[0:1], 0x110
	s_ashr_i32 s7, s6, 31
	s_lshl_b64 s[26:27], s[6:7], 12
	v_and_b32_e32 v36, 63, v34
	s_waitcnt lgkmcnt(0)
	v_lshl_add_u64 v[122:123], s[34:35], 0, v[0:1]
	v_lshlrev_b32_e32 v0, 1, v35
	s_add_u32 s26, s34, s26
	v_lshl_add_u64 v[124:125], s[28:29], 0, v[0:1]
	v_lshl_add_u64 v[126:127], s[20:21], 0, v[0:1]
	v_lshlrev_b32_e32 v0, 4, v36
	s_addc_u32 s27, s35, s27
	v_lshl_add_u64 v[34:35], s[26:27], 0, v[0:1]
	s_mov_b64 s[26:27], 0x800
	v_lshl_add_u64 v[128:129], v[34:35], 0, s[26:27]
	s_lshl_b64 s[26:27], s[6:7], 11
	v_lshl_or_b32 v34, v36, 3, s26
	v_mov_b32_e32 v35, s27
	v_lshl_add_u64 v[36:37], s[28:29], 0, v[34:35]
	s_mov_b64 s[26:27], 0x400
	v_lshl_add_u64 v[34:35], s[20:21], 0, v[34:35]
	v_lshl_add_u64 v[130:131], v[36:37], 0, s[26:27]
	v_lshl_add_u64 v[132:133], v[34:35], 0, s[26:27]
	s_branch .LBB0_50

.Lsw7_x:
	s_mov_b64 exec, s[54:55]
	s_barrier
	s_add_i32 s7, s6, s7
	s_min_i32 s18, s7, 0x4000
	s_cmp_lt_i32 s6, s18
	s_cbranch_scc0 .LBB0_157
	s_load_dwordx2 s[20:21], s[0:1], 0x0
	s_load_dwordx2 s[30:31], s[0:1], 0x90
	s_and_b64 s[28:29], s[22:23], exec
	v_lshlrev_b32_e32 v36, 1, v35
	v_mov_b32_e32 v37, v1
	v_lshl_add_u64 v[128:129], s[26:27], 0, v[36:37]
	s_waitcnt lgkmcnt(0)
	s_cselect_b32 s21, s31, s21
	s_cselect_b32 s20, s30, s20
	s_ashr_i32 s7, s6, 31
	s_lshl_b64 s[34:35], s[6:7], 12
	s_add_u32 s28, s20, s34
	v_lshl_add_u64 v[122:123], s[20:21], 0, v[0:1]
	s_addc_u32 s29, s21, s35
	s_lshl_b64 s[20:21], s[6:7], 11
	s_add_u32 s26, s26, s20
	s_addc_u32 s27, s27, s21
	v_lshl_add_u64 v[126:127], s[30:31], 0, v[0:1]
	s_add_u32 s30, s30, s34
	s_addc_u32 s31, s31, s35
	v_lshl_add_u64 v[124:125], s[24:25], 0, v[36:37]
	v_and_b32_e32 v34, 63, v34
	s_add_u32 s24, s24, s20
	v_lshlrev_b32_e32 v0, 4, v34
	v_lshlrev_b32_e32 v130, 3, v34
	v_mov_b32_e32 v131, v1
	s_addc_u32 s25, s25, s21
	s_branch .LBB0_143

.LBB0_175:
	s_andn2_b64 vcc, exec, s[6:7]
	s_cbranch_vccnz .LBB0_199
	s_cmpk_gt_i32 s3, 0xfff
	s_cbranch_scc1 .LBB0_199
	s_load_dwordx8 s[36:43], s[0:1], 0x38
	s_load_dwordx16 s[48:63], s[0:1], 0xc0
	s_and_b64 s[6:7], s[22:23], exec
	s_cselect_b32 s18, 0x400, 0
	s_load_dwordx2 s[24:25], s[0:1], 0x120
	s_load_dwordx2 s[26:27], s[0:1], 0x100
	s_waitcnt lgkmcnt(0)
	s_add_u32 s89, s42, s18
	s_addc_u32 s90, s43, 0
	s_and_b64 s[6:7], s[22:23], exec
	s_cselect_b32 s6, 0x600, 0
	s_add_u32 s20, s40, s6
	s_addc_u32 s21, s41, 0
	s_and_b64 s[6:7], s[22:23], exec
	s_cselect_b32 s6, 0x4000, 0
	s_add_u32 s28, s36, s6
	s_addc_u32 s29, s37, 0
	s_add_u32 s30, s38, s18
	s_addc_u32 s31, s39, 0
	s_mov_b32 s18, s3
	v_mov_b32_e32 v247, 0
	s_branch .LBB0_181

.LBB0_181:
	s_cmpk_gt_i32 s18, 0x5ff
	s_mov_b64 s[6:7], -1
	s_cbranch_scc0 .LBB0_187
	v_readfirstlane_b32 s6, v247
	s_cmp_lg_u32 s6, 0
	s_cbranch_scc1 .Lsw5_done
	v_mov_b32_e32 v247, 1
	s_mov_b64 s[34:35], exec
	v_readlane_b32 vcc_lo, v244, 7
	v_readlane_b32 vcc_hi, v244, 8
	v_readlane_b32 s36, v244, 48
	v_readlane_b32 s37, v244, 49
	s_nop 1
	s_and_b64 exec, exec, vcc
	s_cbranch_execz .Lsw5_x
	ds_read_b32 v245, v157
	ds_read_b32 v246, v157 offset:4
	s_waitcnt lgkmcnt(0)
	v_readfirstlane_b32 s38, v245
	v_readfirstlane_b32 s39, v246
	s_mul_i32 s38, s38, s39
	s_mov_b32 s39, 0
.Lsw5_l:
	global_load_dword v245, v1, s[36:37] sc1
	s_add_i32 s39, s39, 1
	s_waitcnt vmcnt(0)
	v_readfirstlane_b32 vcc_lo, v245
	s_cmp_ge_u32 vcc_lo, s38
	s_cbranch_scc1 .Lsw5_x
	s_bitcmp1_b32 s39, 16
	s_cbranch_scc0 .Lsw5_l
.Lsw5_x:
	s_mov_b64 exec, s[34:35]
	s_barrier
.Lsw5_done:
	s_add_i32 s6, s18, 0xfffffa00
	s_mul_i32 s7, s6, 0xcccd
	s_lshr_b32 s6, s6, 6
	s_lshr_b32 s40, s7, 25
	s_mul_i32 s7, s6, 0xcd
	s_bfe_u32 s7, s7, 0x5000b
	s_mul_i32 s7, s7, 10
	s_sub_i32 s6, s6, s7
	s_nop 0
	v_mov_b32_e32 v53, v154
	s_and_b32 s37, s6, 0xff
	s_and_b32 s41, s18, 63
	s_lshl_b32 s34, s40, 12
	v_readfirstlane_b32 s6, v53
	s_lshl_b32 s35, s41, 6
	s_ashr_i32 s36, s6, 2
	s_or_b32 s34, s34, s35
	s_and_b32 s35, s36, -16
	s_ashr_i32 s6, s35, 31
	s_add_u32 s72, s35, s34
	v_and_b32_e32 v60, 63, v53
	s_addc_u32 s6, s6, 0
	s_lshl_b32 s34, s37, 6
	v_or_b32_e32 v0, s34, v60
	s_mul_hi_i32 s38, s72, 0x280
	s_mul_i32 s39, s72, 0x280
	v_or_b32_e32 v2, s39, v0
	v_mov_b32_e32 v3, s38
	v_lshlrev_b64 v[2:3], 1, v[2:3]
	v_lshl_add_u64 v[4:5], s[50:51], 0, v[2:3]
	v_add_co_u32_e32 v6, vcc, s88, v4
	v_lshl_add_u64 v[2:3], s[52:53], 0, v[2:3]
	s_nop 0
	v_addc_co_u32_e32 v7, vcc, 0, v5, vcc
	v_add_co_u32_e32 v8, vcc, s88, v2
	s_movk_i32 s42, 0x2000
	s_nop 0
	v_addc_co_u32_e32 v9, vcc, 0, v3, vcc
	s_add_u32 s39, s39, 0x1400
	s_barrier
	global_load_ushort v93, v[4:5], off
	global_load_ushort v91, v[4:5], off offset:1280
	global_load_ushort v89, v[4:5], off offset:2560
	global_load_ushort v87, v[4:5], off offset:3840
	global_load_ushort v94, v[2:3], off
	global_load_ushort v92, v[2:3], off offset:1280
	global_load_ushort v90, v[2:3], off offset:2560
	global_load_ushort v88, v[2:3], off offset:3840
	global_load_ushort v85, v[6:7], off offset:1024
	global_load_ushort v83, v[6:7], off offset:2304
	global_load_ushort v80, v[6:7], off offset:3584
	global_load_ushort v86, v[8:9], off offset:1024
	global_load_ushort v84, v[8:9], off offset:2304
	global_load_ushort v79, v[8:9], off offset:3584
	v_add_co_u32_e32 v6, vcc, s42, v4
	s_addc_u32 s38, s38, 0
	s_nop 0
	v_addc_co_u32_e32 v7, vcc, 0, v5, vcc
	v_or_b32_e32 v10, s39, v0
	v_mov_b32_e32 v11, s38
	v_add_co_u32_e32 v8, vcc, s42, v2
	v_lshlrev_b64 v[10:11], 1, v[10:11]
	s_nop 0
	v_addc_co_u32_e32 v9, vcc, 0, v3, vcc
	v_lshl_add_u64 v[12:13], s[50:51], 0, v[10:11]
	v_lshl_add_u64 v[10:11], s[52:53], 0, v[10:11]
	s_movk_i32 s38, 0x3000
	global_load_ushort v78, v[12:13], off
	global_load_ushort v77, v[10:11], off
	global_load_ushort v82, v[6:7], off offset:768
	global_load_ushort v76, v[6:7], off offset:3328
	global_load_ushort v81, v[8:9], off offset:768
	global_load_ushort v75, v[8:9], off offset:3328
	v_add_co_u32_e32 v6, vcc, s38, v4
	s_mul_i32 s7, s40, 10
	s_nop 0
	v_addc_co_u32_e32 v7, vcc, 0, v5, vcc
	v_add_co_u32_e32 v8, vcc, s38, v2
	s_add_i32 s7, s7, s37
	s_nop 0
	v_addc_co_u32_e32 v9, vcc, 0, v3, vcc
	v_add_co_u32_e32 v4, vcc, s47, v4
	v_ashrrev_i32_e32 v20, 3, v53
	s_nop 0
	v_addc_co_u32_e32 v5, vcc, 0, v5, vcc
	v_add_co_u32_e32 v2, vcc, s47, v2
	v_lshlrev_b32_e32 v0, 3, v53
	s_lshl_b32 s66, s7, 6
	s_lshl_b32 s7, s41, 7
	v_addc_co_u32_e32 v3, vcc, 0, v3, vcc
	v_and_b32_e32 v61, 56, v0
	v_ashrrev_i32_e32 v21, 31, v20
	s_add_u32 s38, s54, s7
	global_load_ushort v73, v[6:7], off offset:512
	global_load_ushort v71, v[6:7], off offset:1792
	global_load_ushort v70, v[6:7], off offset:3072
	global_load_ushort v74, v[8:9], off offset:512
	global_load_ushort v72, v[8:9], off offset:1792
	global_load_ushort v69, v[8:9], off offset:3072
	global_load_ushort v67, v[4:5], off offset:256
	global_load_ushort v64, v[4:5], off offset:1536
	global_load_ushort v63, v[4:5], off offset:2816
	global_load_ushort v68, v[2:3], off offset:256
	global_load_ushort v65, v[2:3], off offset:1536
	global_load_ushort v62, v[2:3], off offset:2816
	v_lshl_add_u64 v[2:3], v[20:21], 0, s[66:67]
	s_addc_u32 s39, s55, 0
	v_lshlrev_b32_e32 v0, 1, v61
	s_or_b32 s7, s66, s41
	v_lshl_add_u64 v[4:5], s[38:39], 0, v[0:1]
	s_lshl_b32 s7, s7, 13
	v_lshlrev_b64 v[2:3], 13, v[2:3]
	s_add_u32 s38, s24, s7
	v_lshl_add_u64 v[10:11], v[4:5], 0, v[2:3]
	s_mov_b32 s7, 0x40000
	s_addc_u32 s39, s25, 0
	global_load_dwordx4 v[2:5], v[10:11], off
	v_add_co_u32_e32 v10, vcc, s7, v10
	s_lshl_b32 s7, s37, 8
	v_lshl_add_u64 v[14:15], s[38:39], 0, v[0:1]
	s_add_u32 s38, s89, s7
	s_addc_u32 s39, s90, 0
	s_add_u32 s66, s38, 0xfffffa00
	s_addc_u32 s73, s39, -1
	s_add_u32 s7, s20, s7
	s_addc_u32 s74, s21, 0
	s_cmp_lt_u32 s37, 6
	s_cselect_b64 s[38:39], -1, 0
	v_lshlrev_b32_e32 v16, 6, v20
	v_bfe_u32 v66, v53, 4, 2
	s_and_b64 s[42:43], s[38:39], exec
	v_ashrrev_i32_e32 v17, 31, v16
	s_cselect_b32 s43, s74, s73
	s_cselect_b32 s42, s7, s66
	v_lshlrev_b32_e32 v59, 2, v66
	s_lshl_b32 s7, s37, 7
	v_and_b32_e32 v54, 15, v53
	v_lshl_add_u64 v[6:7], v[16:17], 1, v[14:15]
	v_add_u32_e32 v16, 0x800, v16
	v_or_b32_e32 v18, s72, v59
	s_add_u32 s72, s56, s7
	v_ashrrev_i32_e32 v17, 31, v16
	s_addc_u32 s73, s57, 0
	v_lshlrev_b32_e32 v0, 1, v54
	v_addc_co_u32_e32 v11, vcc, 0, v11, vcc
	v_lshl_add_u64 v[14:15], v[16:17], 1, v[14:15]
	v_lshl_add_u64 v[22:23], s[72:73], 0, v[0:1]
	v_lshlrev_b32_e32 v19, 2, v54
	s_movk_i32 s7, 0x500
	global_load_dwordx4 v[6:9], v[6:7], off nt
	v_mad_i64_i32 v[22:23], s[72:73], v18, s7, v[22:23]
	global_load_dwordx4 v[10:13], v[10:11], off
	v_mov_b32_e32 v99, v154
	global_load_dwordx4 v[14:17], v[14:15], off nt
	s_nop 0
	global_load_dword v40, v19, s[42:43]
	global_load_dword v39, v19, s[42:43] offset:64
	global_load_dword v38, v19, s[42:43] offset:128
	global_load_dword v21, v19, s[42:43] offset:192
	global_load_ushort v58, v[22:23], off
	global_load_ushort v52, v[22:23], off offset:1280
	global_load_ushort v55, v[22:23], off offset:32
	global_load_ushort v51, v[22:23], off offset:1312
	global_load_ushort v56, v[22:23], off offset:64
	global_load_ushort v50, v[22:23], off offset:1344
	global_load_ushort v49, v[22:23], off offset:1376
	global_load_ushort v57, v[22:23], off offset:96
	global_load_ushort v48, v[22:23], off offset:2560
	global_load_ushort v44, v[22:23], off offset:3840
	global_load_ushort v45, v[22:23], off offset:2592
	global_load_ushort v43, v[22:23], off offset:3872
	global_load_ushort v46, v[22:23], off offset:2624
	global_load_ushort v42, v[22:23], off offset:3904
	global_load_ushort v41, v[22:23], off offset:3936
	global_load_ushort v47, v[22:23], off offset:2656
	v_mov_b32_e32 v19, s6
	v_readfirstlane_b32 s43, v99
	s_ashr_i32 s42, s43, 6
	s_cmp_gt_u32 s37, 5
	s_mov_b64 s[6:7], -1
	s_cbranch_scc0 .LBB0_184
	s_lshl_b32 s6, s40, 18
	s_add_u32 s6, s26, s6
	s_addc_u32 s7, s27, 0
	s_lshl_b32 s40, s41, 12
	s_add_u32 s6, s6, s40
	v_lshlrev_b32_e32 v22, 2, v99
	s_addc_u32 s7, s7, 0
	v_ashrrev_i32_e32 v23, 31, v22
	v_and_b32_e32 v28, 63, v99
	v_lshl_add_u64 v[22:23], v[22:23], 2, s[6:7]
	s_add_i32 s6, s34, 0xfffffe80
	global_load_dwordx4 v[106:109], v[22:23], off
	v_or_b32_e32 v22, s6, v28
	v_mov_b32_e32 v23, v1
	v_lshlrev_b64 v[26:27], 2, v[22:23]
	v_lshl_add_u64 v[30:31], s[28:29], 0, v[26:27]
	s_movk_i32 s6, 0x2000
	v_add_co_u32_e32 v110, vcc, s6, v30
	s_movk_i32 s6, 0x3000
	s_nop 0
	v_addc_co_u32_e32 v111, vcc, 0, v31, vcc
	v_add_co_u32_e32 v34, vcc, s6, v30
	global_load_dword v22, v[110:111], off offset:2048
	global_load_dword v23, v[110:111], off offset:3072
	v_addc_co_u32_e32 v35, vcc, 0, v31, vcc
	global_load_dword v32, v[30:31], off
	global_load_dword v24, v[34:35], off
	v_lshl_add_u64 v[26:27], s[30:31], 0, v[26:27]
	global_load_dword v29, v[26:27], off
	global_load_dword v25, v[34:35], off offset:1024
	s_nop 0
	global_load_dword v26, v[34:35], off offset:2048
	global_load_dword v27, v[34:35], off offset:3072
	global_load_dword v95, v[30:31], off offset:1024
	global_load_dword v96, v[30:31], off offset:2048
	global_load_dword v97, v[30:31], off offset:3072
	global_load_dword v37, v[110:111], off offset:-4096
	v_add_co_u32_e32 v30, vcc, s88, v30
	s_lshl_b32 s6, s42, 10
	s_nop 0
	v_addc_co_u32_e32 v31, vcc, 0, v31, vcc
	global_load_dword v34, v[30:31], off offset:1024
	global_load_dword v35, v[30:31], off offset:2048
	global_load_dword v36, v[30:31], off offset:3072
	s_nop 0
	global_load_dword v30, v[110:111], off
	global_load_dword v31, v[110:111], off offset:1024
	v_lshlrev_b32_e32 v99, 4, v99
	v_mov_b32_e32 v33, s6
	s_and_b32 s6, s43, 0x3fffffc0
	s_cmp_gt_i32 s42, 0
	s_waitcnt vmcnt(17)
	ds_write_b128 v99, v[106:109] offset:55296
	s_waitcnt lgkmcnt(0)
	s_barrier
	ds_read_b128 v[106:109], v33 offset:55296
	ds_read_b128 v[110:113], v33 offset:55312
	ds_read_b128 v[114:117], v33 offset:55328
	ds_read_b128 v[118:121], v33 offset:55344
	ds_read_b128 v[122:125], v33 offset:55360
	ds_read_b128 v[126:129], v33 offset:55376
	ds_read_b128 v[130:133], v33 offset:55392
	ds_read_b128 v[134:137], v33 offset:55408
	s_waitcnt vmcnt(15) lgkmcnt(5)
	v_pk_mul_f32 v[116:117], v[22:23], v[116:117]
	s_waitcnt vmcnt(9) lgkmcnt(4)
	v_pk_mul_f32 v[120:121], v[26:27], v[120:121]
	v_fma_f32 v99, v32, v106, v29
	s_waitcnt vmcnt(8)
	v_fmac_f32_e32 v99, v95, v107
	s_waitcnt vmcnt(7)
	v_fmac_f32_e32 v99, v96, v108
	s_waitcnt vmcnt(6)
	v_fmac_f32_e32 v99, v97, v109
	s_waitcnt vmcnt(5)
	v_fmac_f32_e32 v99, v37, v110
	s_waitcnt lgkmcnt(3)
	v_fma_f32 v101, v32, v122, v29
	s_waitcnt vmcnt(4)
	v_fmac_f32_e32 v99, v34, v111
	v_fmac_f32_e32 v101, v95, v123
	s_waitcnt vmcnt(3)
	v_fmac_f32_e32 v99, v35, v112
	v_fmac_f32_e32 v101, v96, v124
	s_waitcnt vmcnt(2)
	v_fmac_f32_e32 v99, v36, v113
	v_fmac_f32_e32 v101, v97, v125
	s_waitcnt vmcnt(1)
	v_fmac_f32_e32 v99, v30, v114
	s_waitcnt lgkmcnt(2)
	v_fmac_f32_e32 v101, v37, v126
	s_waitcnt vmcnt(0)
	v_fmac_f32_e32 v99, v31, v115
	v_fmac_f32_e32 v101, v34, v127
	v_add_f32_e32 v99, v99, v116
	v_pk_mul_f32 v[118:119], v[24:25], v[118:119]
	v_fmac_f32_e32 v101, v35, v128
	v_add_f32_e32 v99, v99, v117
	v_fmac_f32_e32 v101, v36, v129
	v_add_f32_e32 v99, v99, v118
	s_waitcnt lgkmcnt(1)
	v_fmac_f32_e32 v101, v30, v130
	v_add_f32_e32 v99, v99, v119
	v_pk_mul_f32 v[132:133], v[22:23], v[132:133]
	v_fmac_f32_e32 v101, v31, v131
	v_add_f32_e32 v99, v99, v120
	v_add_f32_e32 v101, v101, v132
	v_add_f32_e32 v99, v99, v121
	s_waitcnt lgkmcnt(0)
	v_pk_mul_f32 v[134:135], v[24:25], v[134:135]
	v_add_f32_e32 v101, v101, v133
	v_mul_f32_e64 v103, |v99|, s46
	v_add_f32_e32 v101, v101, v134
	v_exp_f32_e32 v103, v103
	v_pk_mul_f32 v[136:137], v[26:27], v[136:137]
	v_add_f32_e32 v101, v101, v135
	v_add_f32_e32 v101, v101, v136
	v_add_f32_e32 v101, v101, v137
	v_mul_f32_e64 v105, |v101|, s46
	v_add_f32_e32 v103, 1.0, v103
	v_exp_f32_e32 v105, v105
	v_cmp_gt_f32_e32 vcc, s84, v103
	ds_read_b128 v[106:109], v33 offset:55424
	v_max_f32_e64 v99, -v99, 0
	v_cndmask_b32_e64 v110, 0, 32, vcc
	v_ldexp_f32 v103, v103, v110
	v_log_f32_e32 v103, v103
	v_add_f32_e32 v105, 1.0, v105
	v_cmp_gt_f32_e64 s[40:41], s84, v105
	v_cndmask_b32_e32 v110, 0, v161, vcc
	v_cmp_lt_f32_e64 vcc, |v103|, s45
	v_cndmask_b32_e64 v111, 0, 32, s[40:41]
	v_ldexp_f32 v105, v105, v111
	v_mul_f32_e32 v111, 0x3f317217, v103
	v_log_f32_e32 v105, v105
	v_fma_f32 v111, v103, s44, -v111
	v_fmac_f32_e32 v111, 0x3377d1cf, v103
	v_fmac_f32_e32 v111, 0x3f317217, v103
	v_cndmask_b32_e32 v103, v103, v111, vcc
	v_mul_f32_e32 v112, 0x3f317217, v105
	v_sub_f32_e32 v103, v103, v110
	v_add_f32_e32 v99, v99, v103
	v_fma_f32 v103, v105, s44, -v112
	ds_read_b128 v[110:113], v33 offset:55440
	s_waitcnt lgkmcnt(1)
	v_fma_f32 v114, v32, v106, v29
	v_fmac_f32_e32 v114, v95, v107
	v_fmac_f32_e32 v114, v96, v108
	v_fmac_f32_e32 v114, v97, v109
	s_waitcnt lgkmcnt(0)
	v_fmac_f32_e32 v114, v37, v110
	ds_read_b128 v[106:109], v33 offset:55456
	v_fmac_f32_e32 v114, v34, v111
	v_fmac_f32_e32 v114, v35, v112
	v_fmac_f32_e32 v114, v36, v113
	ds_read_b128 v[110:113], v33 offset:55472
	s_waitcnt lgkmcnt(1)
	v_fmac_f32_e32 v114, v30, v106
	v_fmac_f32_e32 v114, v31, v107
	v_pk_mul_f32 v[106:107], v[22:23], v[108:109]
	v_fmac_f32_e32 v103, 0x3377d1cf, v105
	v_add_f32_e32 v106, v114, v106
	v_add_f32_e32 v108, v106, v107
	s_waitcnt lgkmcnt(0)
	v_pk_mul_f32 v[106:107], v[24:25], v[110:111]
	v_fmac_f32_e32 v103, 0x3f317217, v105
	v_add_f32_e32 v106, v108, v106
	v_add_f32_e32 v108, v106, v107
	v_pk_mul_f32 v[106:107], v[26:27], v[112:113]
	v_cmp_lt_f32_e64 vcc, |v105|, s45
	v_add_f32_e32 v106, v108, v106
	v_add_f32_e32 v106, v106, v107
	v_mul_f32_e64 v107, |v106|, s46
	v_exp_f32_e32 v107, v107
	v_cndmask_b32_e32 v103, v105, v103, vcc
	v_cndmask_b32_e64 v105, 0, v161, s[40:41]
	v_max_f32_e64 v101, -v101, 0
	v_add_f32_e32 v107, 1.0, v107
	v_cmp_gt_f32_e32 vcc, s84, v107
	v_sub_f32_e32 v103, v103, v105
	v_add_f32_e32 v101, v101, v103
	v_cndmask_b32_e64 v108, 0, 32, vcc
	v_ldexp_f32 v107, v107, v108
	v_log_f32_e32 v114, v107
	v_max_f32_e64 v103, -v106, 0
	ds_read_b128 v[106:109], v33 offset:55488
	ds_read_b128 v[110:113], v33 offset:55504
	v_mul_f32_e32 v105, 0x3f317217, v114
	v_fma_f32 v105, v114, s44, -v105
	v_fmac_f32_e32 v105, 0x3377d1cf, v114
	s_waitcnt lgkmcnt(1)
	v_fma_f32 v115, v32, v106, v29
	v_fmac_f32_e32 v115, v95, v107
	v_fmac_f32_e32 v115, v96, v108
	v_fmac_f32_e32 v115, v97, v109
	s_waitcnt lgkmcnt(0)
	v_fmac_f32_e32 v115, v37, v110
	ds_read_b128 v[106:109], v33 offset:55520
	v_fmac_f32_e32 v115, v34, v111
	v_fmac_f32_e32 v115, v35, v112
	v_fmac_f32_e32 v115, v36, v113
	ds_read_b128 v[110:113], v33 offset:55536
	s_waitcnt lgkmcnt(1)
	v_fmac_f32_e32 v115, v30, v106
	v_fmac_f32_e32 v115, v31, v107
	v_pk_mul_f32 v[106:107], v[22:23], v[108:109]
	v_fmac_f32_e32 v105, 0x3f317217, v114
	v_add_f32_e32 v106, v115, v106
	v_add_f32_e32 v108, v106, v107
	s_waitcnt lgkmcnt(0)
	v_pk_mul_f32 v[106:107], v[24:25], v[110:111]
	v_cmp_lt_f32_e64 s[40:41], |v114|, s45
	v_add_f32_e32 v106, v108, v106
	v_add_f32_e32 v108, v106, v107
	v_pk_mul_f32 v[106:107], v[26:27], v[112:113]
	v_cndmask_b32_e64 v105, v114, v105, s[40:41]
	v_add_f32_e32 v106, v108, v106
	v_add_f32_e32 v106, v106, v107
	v_mul_f32_e64 v107, |v106|, s46
	v_exp_f32_e32 v107, v107
	v_cndmask_b32_e32 v108, 0, v161, vcc
	v_sub_f32_e32 v105, v105, v108
	v_add_f32_e32 v103, v103, v105
	v_add_f32_e32 v107, 1.0, v107
	v_cmp_gt_f32_e32 vcc, s84, v107
	v_max_f32_e64 v105, -v106, 0
	s_nop 0
	v_cndmask_b32_e64 v109, 0, 32, vcc
	v_ldexp_f32 v107, v107, v109
	v_log_f32_e32 v114, v107
	ds_read_b128 v[106:109], v33 offset:55552
	v_mul_f32_e32 v110, 0x3f317217, v114
	v_fma_f32 v115, v114, s44, -v110
	ds_read_b128 v[110:113], v33 offset:55568
	s_waitcnt lgkmcnt(1)
	v_fma_f32 v116, v32, v106, v29
	v_fmac_f32_e32 v116, v95, v107
	v_fmac_f32_e32 v116, v96, v108
	v_fmac_f32_e32 v116, v97, v109
	s_waitcnt lgkmcnt(0)
	v_fmac_f32_e32 v116, v37, v110
	ds_read_b128 v[106:109], v33 offset:55584
	v_fmac_f32_e32 v116, v34, v111
	v_fmac_f32_e32 v116, v35, v112
	v_fmac_f32_e32 v116, v36, v113
	ds_read_b128 v[110:113], v33 offset:55600
	s_waitcnt lgkmcnt(1)
	v_fmac_f32_e32 v116, v30, v106
	v_fmac_f32_e32 v116, v31, v107
	v_pk_mul_f32 v[106:107], v[22:23], v[108:109]
	v_fmac_f32_e32 v115, 0x3377d1cf, v114
	v_add_f32_e32 v106, v116, v106
	v_add_f32_e32 v108, v106, v107
	s_waitcnt lgkmcnt(0)
	v_pk_mul_f32 v[106:107], v[24:25], v[110:111]
	v_cndmask_b32_e32 v109, 0, v161, vcc
	v_add_f32_e32 v106, v108, v106
	v_add_f32_e32 v108, v106, v107
	v_pk_mul_f32 v[106:107], v[26:27], v[112:113]
	v_fmac_f32_e32 v115, 0x3f317217, v114
	v_add_f32_e32 v106, v108, v106
	v_add_f32_e32 v106, v106, v107
	v_mul_f32_e64 v107, |v106|, s46
	v_exp_f32_e32 v107, v107
	v_cmp_lt_f32_e64 s[40:41], |v114|, s45
	v_add_f32_e32 v107, 1.0, v107
	v_cmp_gt_f32_e32 vcc, s84, v107
	v_cndmask_b32_e64 v108, v114, v115, s[40:41]
	v_max_f32_e64 v115, -v106, 0
	v_cndmask_b32_e64 v110, 0, 32, vcc
	v_ldexp_f32 v107, v107, v110
	v_log_f32_e32 v114, v107
	v_sub_f32_e32 v107, v108, v109
	v_add_f32_e32 v105, v105, v107
	ds_read_b128 v[106:109], v33 offset:55616
	v_mul_f32_e32 v110, 0x3f317217, v114
	v_fma_f32 v116, v114, s44, -v110
	ds_read_b128 v[110:113], v33 offset:55632
	v_fmac_f32_e32 v116, 0x3377d1cf, v114
	s_waitcnt lgkmcnt(1)
	v_fma_f32 v117, v32, v106, v29
	v_fmac_f32_e32 v117, v95, v107
	v_fmac_f32_e32 v117, v96, v108
	v_fmac_f32_e32 v117, v97, v109
	s_waitcnt lgkmcnt(0)
	v_fmac_f32_e32 v117, v37, v110
	ds_read_b128 v[106:109], v33 offset:55648
	v_fmac_f32_e32 v117, v34, v111
	v_fmac_f32_e32 v117, v35, v112
	v_fmac_f32_e32 v117, v36, v113
	ds_read_b128 v[110:113], v33 offset:55664
	s_waitcnt lgkmcnt(1)
	v_fmac_f32_e32 v117, v30, v106
	v_fmac_f32_e32 v117, v31, v107
	v_pk_mul_f32 v[106:107], v[22:23], v[108:109]
	v_cndmask_b32_e32 v109, 0, v161, vcc
	v_add_f32_e32 v106, v117, v106
	v_add_f32_e32 v108, v106, v107
	s_waitcnt lgkmcnt(0)
	v_pk_mul_f32 v[106:107], v[24:25], v[110:111]
	v_fmac_f32_e32 v116, 0x3f317217, v114
	v_add_f32_e32 v106, v108, v106
	v_add_f32_e32 v108, v106, v107
	v_pk_mul_f32 v[106:107], v[26:27], v[112:113]
	v_cmp_lt_f32_e64 s[40:41], |v114|, s45
	v_add_f32_e32 v106, v108, v106
	v_add_f32_e32 v107, v106, v107
	v_mul_f32_e64 v106, |v107|, s46
	v_exp_f32_e32 v106, v106
	v_cndmask_b32_e64 v108, v114, v116, s[40:41]
	v_max_f32_e64 v107, -v107, 0
	v_add_f32_e32 v106, 1.0, v106
	v_cmp_gt_f32_e32 vcc, s84, v106
	s_nop 1
	v_cndmask_b32_e64 v110, 0, 32, vcc
	v_ldexp_f32 v106, v106, v110
	v_log_f32_e32 v116, v106
	v_sub_f32_e32 v106, v108, v109
	ds_read_b128 v[108:111], v33 offset:55680
	v_add_f32_e32 v106, v115, v106
	v_mul_f32_e32 v112, 0x3f317217, v116
	v_fma_f32 v117, v116, s44, -v112
	ds_read_b128 v[112:115], v33 offset:55696
	s_waitcnt lgkmcnt(1)
	v_fma_f32 v118, v32, v108, v29
	v_fmac_f32_e32 v118, v95, v109
	v_fmac_f32_e32 v118, v96, v110
	v_fmac_f32_e32 v118, v97, v111
	s_waitcnt lgkmcnt(0)
	v_fmac_f32_e32 v118, v37, v112
	ds_read_b128 v[108:111], v33 offset:55712
	v_fmac_f32_e32 v118, v34, v113
	v_fmac_f32_e32 v118, v35, v114
	v_fmac_f32_e32 v118, v36, v115
	ds_read_b128 v[112:115], v33 offset:55728
	s_waitcnt lgkmcnt(1)
	v_fmac_f32_e32 v118, v30, v108
	v_fmac_f32_e32 v118, v31, v109
	v_pk_mul_f32 v[108:109], v[22:23], v[110:111]
	v_fmac_f32_e32 v117, 0x3377d1cf, v116
	v_add_f32_e32 v108, v118, v108
	v_add_f32_e32 v110, v108, v109
	s_waitcnt lgkmcnt(0)
	v_pk_mul_f32 v[108:109], v[24:25], v[112:113]
	v_cndmask_b32_e32 v111, 0, v161, vcc
	v_add_f32_e32 v108, v110, v108
	v_add_f32_e32 v110, v108, v109
	v_pk_mul_f32 v[108:109], v[26:27], v[114:115]
	v_fmac_f32_e32 v117, 0x3f317217, v116
	v_add_f32_e32 v108, v110, v108
	v_add_f32_e32 v108, v108, v109
	v_mul_f32_e64 v109, |v108|, s46
	v_exp_f32_e32 v109, v109
	v_cmp_lt_f32_e64 s[40:41], |v116|, s45
	v_add_f32_e32 v109, 1.0, v109
	v_cmp_gt_f32_e32 vcc, s84, v109
	v_cndmask_b32_e64 v110, v116, v117, s[40:41]
	v_max_f32_e64 v117, -v108, 0
	v_cndmask_b32_e64 v112, 0, 32, vcc
	v_ldexp_f32 v109, v109, v112
	v_log_f32_e32 v116, v109
	v_sub_f32_e32 v109, v110, v111
	v_add_f32_e32 v107, v107, v109
	ds_read_b128 v[108:111], v33 offset:55744
	v_mul_f32_e32 v112, 0x3f317217, v116
	v_fma_f32 v118, v116, s44, -v112
	ds_read_b128 v[112:115], v33 offset:55760
	v_fmac_f32_e32 v118, 0x3377d1cf, v116
	s_waitcnt lgkmcnt(1)
	v_fma_f32 v119, v32, v108, v29
	v_fmac_f32_e32 v119, v95, v109
	v_fmac_f32_e32 v119, v96, v110
	v_fmac_f32_e32 v119, v97, v111
	s_waitcnt lgkmcnt(0)
	v_fmac_f32_e32 v119, v37, v112
	ds_read_b128 v[108:111], v33 offset:55776
	v_fmac_f32_e32 v119, v34, v113
	v_fmac_f32_e32 v119, v35, v114
	v_fmac_f32_e32 v119, v36, v115
	ds_read_b128 v[112:115], v33 offset:55792
	s_waitcnt lgkmcnt(1)
	v_fmac_f32_e32 v119, v30, v108
	v_fmac_f32_e32 v119, v31, v109
	v_pk_mul_f32 v[108:109], v[22:23], v[110:111]
	v_cndmask_b32_e32 v111, 0, v161, vcc
	v_add_f32_e32 v108, v119, v108
	v_add_f32_e32 v110, v108, v109
	s_waitcnt lgkmcnt(0)
	v_pk_mul_f32 v[108:109], v[24:25], v[112:113]
	v_fmac_f32_e32 v118, 0x3f317217, v116
	v_add_f32_e32 v108, v110, v108
	v_add_f32_e32 v110, v108, v109
	v_pk_mul_f32 v[108:109], v[26:27], v[114:115]
	v_cmp_lt_f32_e64 s[40:41], |v116|, s45
	v_add_f32_e32 v108, v110, v108
	v_add_f32_e32 v109, v108, v109
	v_mul_f32_e64 v108, |v109|, s46
	v_exp_f32_e32 v108, v108
	v_cndmask_b32_e64 v110, v116, v118, s[40:41]
	v_max_f32_e64 v109, -v109, 0
	v_add_f32_e32 v108, 1.0, v108
	v_cmp_gt_f32_e32 vcc, s84, v108
	s_nop 1
	v_cndmask_b32_e64 v112, 0, 32, vcc
	v_ldexp_f32 v108, v108, v112
	v_log_f32_e32 v118, v108
	v_sub_f32_e32 v108, v110, v111
	ds_read_b128 v[110:113], v33 offset:55808
	v_add_f32_e32 v108, v117, v108
	v_mul_f32_e32 v114, 0x3f317217, v118
	v_fma_f32 v119, v118, s44, -v114
	ds_read_b128 v[114:117], v33 offset:55824
	s_waitcnt lgkmcnt(1)
	v_fma_f32 v120, v32, v110, v29
	v_fmac_f32_e32 v120, v95, v111
	v_fmac_f32_e32 v120, v96, v112
	v_fmac_f32_e32 v120, v97, v113
	s_waitcnt lgkmcnt(0)
	v_fmac_f32_e32 v120, v37, v114
	ds_read_b128 v[110:113], v33 offset:55840
	v_fmac_f32_e32 v120, v34, v115
	v_fmac_f32_e32 v120, v35, v116
	v_fmac_f32_e32 v120, v36, v117
	ds_read_b128 v[114:117], v33 offset:55856
	s_waitcnt lgkmcnt(1)
	v_fmac_f32_e32 v120, v30, v110
	v_fmac_f32_e32 v120, v31, v111
	v_pk_mul_f32 v[110:111], v[22:23], v[112:113]
	v_fmac_f32_e32 v119, 0x3377d1cf, v118
	v_add_f32_e32 v110, v120, v110
	v_add_f32_e32 v112, v110, v111
	s_waitcnt lgkmcnt(0)
	v_pk_mul_f32 v[110:111], v[24:25], v[114:115]
	v_cndmask_b32_e32 v113, 0, v161, vcc
	v_add_f32_e32 v110, v112, v110
	v_add_f32_e32 v112, v110, v111
	v_pk_mul_f32 v[110:111], v[26:27], v[116:117]
	v_fmac_f32_e32 v119, 0x3f317217, v118
	v_add_f32_e32 v110, v112, v110
	v_add_f32_e32 v110, v110, v111
	v_mul_f32_e64 v111, |v110|, s46
	v_exp_f32_e32 v111, v111
	v_cmp_lt_f32_e64 s[40:41], |v118|, s45
	v_add_f32_e32 v111, 1.0, v111
	v_cmp_gt_f32_e32 vcc, s84, v111
	v_cndmask_b32_e64 v112, v118, v119, s[40:41]
	v_max_f32_e64 v119, -v110, 0
	v_cndmask_b32_e64 v114, 0, 32, vcc
	v_ldexp_f32 v111, v111, v114
	v_log_f32_e32 v118, v111
	v_sub_f32_e32 v111, v112, v113
	v_add_f32_e32 v109, v109, v111
	ds_read_b128 v[110:113], v33 offset:55872
	v_mul_f32_e32 v114, 0x3f317217, v118
	v_fma_f32 v120, v118, s44, -v114
	ds_read_b128 v[114:117], v33 offset:55888
	v_fmac_f32_e32 v120, 0x3377d1cf, v118
	s_waitcnt lgkmcnt(1)
	v_fma_f32 v121, v32, v110, v29
	v_fmac_f32_e32 v121, v95, v111
	v_fmac_f32_e32 v121, v96, v112
	v_fmac_f32_e32 v121, v97, v113
	s_waitcnt lgkmcnt(0)
	v_fmac_f32_e32 v121, v37, v114
	ds_read_b128 v[110:113], v33 offset:55904
	v_fmac_f32_e32 v121, v34, v115
	v_fmac_f32_e32 v121, v35, v116
	v_fmac_f32_e32 v121, v36, v117
	ds_read_b128 v[114:117], v33 offset:55920
	s_waitcnt lgkmcnt(1)
	v_fmac_f32_e32 v121, v30, v110
	v_fmac_f32_e32 v121, v31, v111
	v_pk_mul_f32 v[110:111], v[22:23], v[112:113]
	v_cndmask_b32_e32 v113, 0, v161, vcc
	v_add_f32_e32 v110, v121, v110
	v_add_f32_e32 v112, v110, v111
	s_waitcnt lgkmcnt(0)
	v_pk_mul_f32 v[110:111], v[24:25], v[114:115]
	v_fmac_f32_e32 v120, 0x3f317217, v118
	v_add_f32_e32 v110, v112, v110
	v_add_f32_e32 v112, v110, v111
	v_pk_mul_f32 v[110:111], v[26:27], v[116:117]
	v_cmp_lt_f32_e64 s[40:41], |v118|, s45
	v_add_f32_e32 v110, v112, v110
	v_add_f32_e32 v110, v110, v111
	v_mul_f32_e64 v111, |v110|, s46
	v_exp_f32_e32 v111, v111
	v_cndmask_b32_e64 v112, v118, v120, s[40:41]
	v_max_f32_e64 v120, -v110, 0
	v_add_f32_e32 v111, 1.0, v111
	v_cmp_gt_f32_e32 vcc, s84, v111
	s_nop 1
	v_cndmask_b32_e64 v114, 0, 32, vcc
	v_ldexp_f32 v111, v111, v114
	v_log_f32_e32 v118, v111
	v_sub_f32_e32 v111, v112, v113
	v_add_f32_e32 v119, v119, v111
	ds_read_b128 v[110:113], v33 offset:55936
	v_mul_f32_e32 v114, 0x3f317217, v118
	v_fma_f32 v121, v118, s44, -v114
	ds_read_b128 v[114:117], v33 offset:55952
	v_fmac_f32_e32 v121, 0x3377d1cf, v118
	s_waitcnt lgkmcnt(1)
	v_fma_f32 v122, v32, v110, v29
	v_fmac_f32_e32 v122, v95, v111
	v_fmac_f32_e32 v122, v96, v112
	v_fmac_f32_e32 v122, v97, v113
	s_waitcnt lgkmcnt(0)
	v_fmac_f32_e32 v122, v37, v114
	ds_read_b128 v[110:113], v33 offset:55968
	v_fmac_f32_e32 v122, v34, v115
	v_fmac_f32_e32 v122, v35, v116
	v_fmac_f32_e32 v122, v36, v117
	ds_read_b128 v[114:117], v33 offset:55984
	s_waitcnt lgkmcnt(1)
	v_fmac_f32_e32 v122, v30, v110
	v_fmac_f32_e32 v122, v31, v111
	v_pk_mul_f32 v[110:111], v[22:23], v[112:113]
	v_cndmask_b32_e32 v113, 0, v161, vcc
	v_add_f32_e32 v110, v122, v110
	v_add_f32_e32 v112, v110, v111
	s_waitcnt lgkmcnt(0)
	v_pk_mul_f32 v[110:111], v[24:25], v[114:115]
	v_fmac_f32_e32 v121, 0x3f317217, v118
	v_add_f32_e32 v110, v112, v110
	v_add_f32_e32 v112, v110, v111
	v_pk_mul_f32 v[110:111], v[26:27], v[116:117]
	v_cmp_lt_f32_e64 s[40:41], |v118|, s45
	v_add_f32_e32 v110, v112, v110
	v_add_f32_e32 v110, v110, v111
	v_mul_f32_e64 v111, |v110|, s46
	v_exp_f32_e32 v111, v111
	v_cndmask_b32_e64 v112, v118, v121, s[40:41]
	v_max_f32_e64 v121, -v110, 0
	v_add_f32_e32 v111, 1.0, v111
	v_cmp_gt_f32_e32 vcc, s84, v111
	s_nop 1
	v_cndmask_b32_e64 v114, 0, 32, vcc
	v_ldexp_f32 v111, v111, v114
	v_log_f32_e32 v118, v111
	v_sub_f32_e32 v111, v112, v113
	v_add_f32_e32 v120, v120, v111
	ds_read_b128 v[110:113], v33 offset:56000
	v_mul_f32_e32 v114, 0x3f317217, v118
	v_fma_f32 v122, v118, s44, -v114
	ds_read_b128 v[114:117], v33 offset:56016
	v_fmac_f32_e32 v122, 0x3377d1cf, v118
	s_waitcnt lgkmcnt(1)
	v_fma_f32 v123, v32, v110, v29
	v_fmac_f32_e32 v123, v95, v111
	v_fmac_f32_e32 v123, v96, v112
	v_fmac_f32_e32 v123, v97, v113
	s_waitcnt lgkmcnt(0)
	v_fmac_f32_e32 v123, v37, v114
	ds_read_b128 v[110:113], v33 offset:56032
	v_fmac_f32_e32 v123, v34, v115
	v_fmac_f32_e32 v123, v35, v116
	v_fmac_f32_e32 v123, v36, v117
	ds_read_b128 v[114:117], v33 offset:56048
	s_waitcnt lgkmcnt(1)
	v_fmac_f32_e32 v123, v30, v110
	v_fmac_f32_e32 v123, v31, v111
	v_pk_mul_f32 v[110:111], v[22:23], v[112:113]
	v_cndmask_b32_e32 v113, 0, v161, vcc
	v_add_f32_e32 v110, v123, v110
	v_add_f32_e32 v112, v110, v111
	s_waitcnt lgkmcnt(0)
	v_pk_mul_f32 v[110:111], v[24:25], v[114:115]
	v_fmac_f32_e32 v122, 0x3f317217, v118
	v_add_f32_e32 v110, v112, v110
	v_add_f32_e32 v112, v110, v111
	v_pk_mul_f32 v[110:111], v[26:27], v[116:117]
	v_cmp_lt_f32_e64 s[40:41], |v118|, s45
	v_add_f32_e32 v110, v112, v110
	v_add_f32_e32 v110, v110, v111
	v_mul_f32_e64 v111, |v110|, s46
	v_exp_f32_e32 v111, v111
	v_cndmask_b32_e64 v112, v118, v122, s[40:41]
	v_max_f32_e64 v122, -v110, 0
	v_add_f32_e32 v111, 1.0, v111
	v_cmp_gt_f32_e32 vcc, s84, v111
	s_nop 1
	v_cndmask_b32_e64 v114, 0, 32, vcc
	v_ldexp_f32 v111, v111, v114
	v_log_f32_e32 v118, v111
	v_sub_f32_e32 v111, v112, v113
	v_add_f32_e32 v121, v121, v111
	ds_read_b128 v[110:113], v33 offset:56064
	v_mul_f32_e32 v114, 0x3f317217, v118
	v_fma_f32 v123, v118, s44, -v114
	ds_read_b128 v[114:117], v33 offset:56080
	v_fmac_f32_e32 v123, 0x3377d1cf, v118
	s_waitcnt lgkmcnt(1)
	v_fma_f32 v124, v32, v110, v29
	v_fmac_f32_e32 v124, v95, v111
	v_fmac_f32_e32 v124, v96, v112
	v_fmac_f32_e32 v124, v97, v113
	s_waitcnt lgkmcnt(0)
	v_fmac_f32_e32 v124, v37, v114
	ds_read_b128 v[110:113], v33 offset:56096
	v_fmac_f32_e32 v124, v34, v115
	v_fmac_f32_e32 v124, v35, v116
	v_fmac_f32_e32 v124, v36, v117
	ds_read_b128 v[114:117], v33 offset:56112
	s_waitcnt lgkmcnt(1)
	v_fmac_f32_e32 v124, v30, v110
	v_fmac_f32_e32 v124, v31, v111
	v_pk_mul_f32 v[110:111], v[22:23], v[112:113]
	v_cndmask_b32_e32 v113, 0, v161, vcc
	v_add_f32_e32 v110, v124, v110
	v_add_f32_e32 v112, v110, v111
	s_waitcnt lgkmcnt(0)
	v_pk_mul_f32 v[110:111], v[24:25], v[114:115]
	v_fmac_f32_e32 v123, 0x3f317217, v118
	v_add_f32_e32 v110, v112, v110
	v_add_f32_e32 v112, v110, v111
	v_pk_mul_f32 v[110:111], v[26:27], v[116:117]
	v_cmp_lt_f32_e64 s[40:41], |v118|, s45
	v_add_f32_e32 v110, v112, v110
	v_add_f32_e32 v110, v110, v111
	v_mul_f32_e64 v111, |v110|, s46
	v_exp_f32_e32 v111, v111
	v_cndmask_b32_e64 v112, v118, v123, s[40:41]
	v_max_f32_e64 v123, -v110, 0
	v_add_f32_e32 v111, 1.0, v111
	v_cmp_gt_f32_e32 vcc, s84, v111
	s_nop 1
	v_cndmask_b32_e64 v114, 0, 32, vcc
	v_ldexp_f32 v111, v111, v114
	v_log_f32_e32 v118, v111
	v_sub_f32_e32 v111, v112, v113
	v_add_f32_e32 v122, v122, v111
	ds_read_b128 v[110:113], v33 offset:56128
	v_mul_f32_e32 v114, 0x3f317217, v118
	v_fma_f32 v124, v118, s44, -v114
	ds_read_b128 v[114:117], v33 offset:56144
	v_fmac_f32_e32 v124, 0x3377d1cf, v118
	s_waitcnt lgkmcnt(1)
	v_fma_f32 v125, v32, v110, v29
	v_fmac_f32_e32 v125, v95, v111
	v_fmac_f32_e32 v125, v96, v112
	v_fmac_f32_e32 v125, v97, v113
	s_waitcnt lgkmcnt(0)
	v_fmac_f32_e32 v125, v37, v114
	ds_read_b128 v[110:113], v33 offset:56160
	v_fmac_f32_e32 v125, v34, v115
	v_fmac_f32_e32 v125, v35, v116
	v_fmac_f32_e32 v125, v36, v117
	ds_read_b128 v[114:117], v33 offset:56176
	s_waitcnt lgkmcnt(1)
	v_fmac_f32_e32 v125, v30, v110
	v_fmac_f32_e32 v125, v31, v111
	v_pk_mul_f32 v[110:111], v[22:23], v[112:113]
	v_cndmask_b32_e32 v113, 0, v161, vcc
	v_add_f32_e32 v110, v125, v110
	v_add_f32_e32 v112, v110, v111
	s_waitcnt lgkmcnt(0)
	v_pk_mul_f32 v[110:111], v[24:25], v[114:115]
	v_fmac_f32_e32 v124, 0x3f317217, v118
	v_add_f32_e32 v110, v112, v110
	v_add_f32_e32 v112, v110, v111
	v_pk_mul_f32 v[110:111], v[26:27], v[116:117]
	v_cmp_lt_f32_e64 s[40:41], |v118|, s45
	v_add_f32_e32 v110, v112, v110
	v_add_f32_e32 v110, v110, v111
	v_mul_f32_e64 v111, |v110|, s46
	v_exp_f32_e32 v111, v111
	v_cndmask_b32_e64 v112, v118, v124, s[40:41]
	v_max_f32_e64 v124, -v110, 0
	v_add_f32_e32 v111, 1.0, v111
	v_cmp_gt_f32_e32 vcc, s84, v111
	s_nop 1
	v_cndmask_b32_e64 v114, 0, 32, vcc
	v_ldexp_f32 v111, v111, v114
	v_log_f32_e32 v118, v111
	v_sub_f32_e32 v111, v112, v113
	v_add_f32_e32 v123, v123, v111
	ds_read_b128 v[110:113], v33 offset:56192
	v_mul_f32_e32 v114, 0x3f317217, v118
	v_fma_f32 v125, v118, s44, -v114
	ds_read_b128 v[114:117], v33 offset:56208
	v_fmac_f32_e32 v125, 0x3377d1cf, v118
	s_waitcnt lgkmcnt(1)
	v_fma_f32 v126, v32, v110, v29
	v_fmac_f32_e32 v126, v95, v111
	v_fmac_f32_e32 v126, v96, v112
	v_fmac_f32_e32 v126, v97, v113
	s_waitcnt lgkmcnt(0)
	v_fmac_f32_e32 v126, v37, v114
	ds_read_b128 v[110:113], v33 offset:56224
	v_fmac_f32_e32 v126, v34, v115
	v_fmac_f32_e32 v126, v35, v116
	v_fmac_f32_e32 v126, v36, v117
	ds_read_b128 v[114:117], v33 offset:56240
	s_waitcnt lgkmcnt(1)
	v_fmac_f32_e32 v126, v30, v110
	v_fmac_f32_e32 v126, v31, v111
	v_pk_mul_f32 v[110:111], v[22:23], v[112:113]
	v_cndmask_b32_e32 v113, 0, v161, vcc
	v_add_f32_e32 v110, v126, v110
	v_add_f32_e32 v112, v110, v111
	s_waitcnt lgkmcnt(0)
	v_pk_mul_f32 v[110:111], v[24:25], v[114:115]
	v_fmac_f32_e32 v125, 0x3f317217, v118
	v_add_f32_e32 v110, v112, v110
	v_add_f32_e32 v112, v110, v111
	v_pk_mul_f32 v[110:111], v[26:27], v[116:117]
	v_cmp_lt_f32_e64 s[40:41], |v118|, s45
	v_add_f32_e32 v110, v112, v110
	v_add_f32_e32 v110, v110, v111
	v_mul_f32_e64 v111, |v110|, s46
	v_exp_f32_e32 v111, v111
	v_cndmask_b32_e64 v112, v118, v125, s[40:41]
	v_max_f32_e64 v125, -v110, 0
	v_add_f32_e32 v111, 1.0, v111
	v_cmp_gt_f32_e32 vcc, s84, v111
	s_nop 1
	v_cndmask_b32_e64 v114, 0, 32, vcc
	v_ldexp_f32 v111, v111, v114
	v_log_f32_e32 v118, v111
	v_sub_f32_e32 v111, v112, v113
	v_add_f32_e32 v124, v124, v111
	ds_read_b128 v[110:113], v33 offset:56256
	v_mul_f32_e32 v114, 0x3f317217, v118
	v_fma_f32 v126, v118, s44, -v114
	ds_read_b128 v[114:117], v33 offset:56272
	v_fmac_f32_e32 v126, 0x3377d1cf, v118
	s_waitcnt lgkmcnt(1)
	v_fmac_f32_e32 v29, v32, v110
	v_fmac_f32_e32 v29, v95, v111
	v_fmac_f32_e32 v29, v96, v112
	v_fmac_f32_e32 v29, v97, v113
	ds_read_b128 v[110:113], v33 offset:56288
	s_waitcnt lgkmcnt(1)
	v_fmac_f32_e32 v29, v37, v114
	v_fmac_f32_e32 v29, v34, v115
	v_fmac_f32_e32 v29, v35, v116
	ds_read_b128 v[32:35], v33 offset:56304
	v_fmac_f32_e32 v29, v36, v117
	s_waitcnt lgkmcnt(1)
	v_fmac_f32_e32 v29, v30, v110
	v_fmac_f32_e32 v29, v31, v111
	v_pk_mul_f32 v[22:23], v[22:23], v[112:113]
	v_lshlrev_b32_e32 v110, 2, v28
	v_add_f32_e32 v22, v29, v22
	v_add_f32_e32 v29, v22, v23
	s_waitcnt lgkmcnt(0)
	v_pk_mul_f32 v[22:23], v[24:25], v[32:33]
	v_lshl_or_b32 v96, s6, 2, v110
	v_add_f32_e32 v22, v29, v22
	v_add_f32_e32 v24, v22, v23
	v_pk_mul_f32 v[22:23], v[26:27], v[34:35]
	s_mov_b32 s6, 0xbd800000
	v_add_f32_e32 v22, v24, v22
	v_add_f32_e32 v22, v22, v23
	v_mul_f32_e64 v23, |v22|, s46
	v_exp_f32_e32 v23, v23
	v_cndmask_b32_e32 v25, 0, v161, vcc
	v_fma_f32 v36, v99, s6, 0
	v_fmamk_f32 v37, v101, 0xbd800000, v36
	v_add_f32_e32 v23, 1.0, v23
	v_cmp_gt_f32_e32 vcc, s84, v23
	v_fmamk_f32 v34, v103, 0xbd800000, v37
	v_fmamk_f32 v35, v105, 0xbd800000, v34
	v_cndmask_b32_e64 v26, 0, 32, vcc
	v_ldexp_f32 v23, v23, v26
	v_log_f32_e32 v23, v23
	v_fmac_f32_e32 v126, 0x3f317217, v118
	v_cmp_lt_f32_e64 s[40:41], |v118|, s45
	v_fmamk_f32 v32, v106, 0xbd800000, v35
	v_fmamk_f32 v33, v107, 0xbd800000, v32
	v_cndmask_b32_e64 v24, v118, v126, s[40:41]
	v_sub_f32_e32 v24, v24, v25
	v_fmamk_f32 v30, v108, 0xbd800000, v33
	v_add_f32_e32 v95, v125, v24
	v_mul_f32_e32 v24, 0x3f317217, v23
	v_fmamk_f32 v31, v109, 0xbd800000, v30
	v_fma_f32 v24, v23, s44, -v24
	v_fmamk_f32 v28, v119, 0xbd800000, v31
	v_fmac_f32_e32 v24, 0x3377d1cf, v23
	v_fmamk_f32 v29, v120, 0xbd800000, v28
	v_fmac_f32_e32 v24, 0x3f317217, v23
	v_cmp_lt_f32_e64 s[40:41], |v23|, s45
	v_fmamk_f32 v26, v121, 0xbd800000, v29
	v_fmamk_f32 v27, v122, 0xbd800000, v26
	v_cndmask_b32_e64 v23, v23, v24, s[40:41]
	v_cndmask_b32_e32 v24, 0, v161, vcc
	v_sub_f32_e32 v23, v23, v24
	v_fmamk_f32 v24, v123, 0xbd800000, v27
	v_max_f32_e64 v22, -v22, 0
	v_fmamk_f32 v25, v124, 0xbd800000, v24
	v_add_f32_e32 v23, v22, v23
	v_fmamk_f32 v22, v95, 0xbd800000, v25
	v_fmamk_f32 v23, v23, 0xbd800000, v22
	ds_write_b32 v96, v23 offset:59392
	s_waitcnt lgkmcnt(0)
	s_barrier
	ds_read2st64_b32 v[96:97], v110 offset0:232 offset1:233
	ds_read2st64_b32 v[106:107], v110 offset0:234 offset1:235
	s_cselect_b64 vcc, -1, 0
	s_cmp_gt_i32 s42, 1
	s_mov_b64 s[6:7], 0
	s_waitcnt lgkmcnt(1)
	v_add_f32_e32 v95, 0, v96
	v_cndmask_b32_e32 v95, 0, v95, vcc
	v_add_f32_e32 v96, v97, v95
	s_cselect_b64 vcc, -1, 0
	s_cmp_gt_i32 s42, 2
	v_cndmask_b32_e32 v95, v95, v96, vcc
	s_waitcnt lgkmcnt(0)
	v_add_f32_e32 v96, v106, v95
	s_cselect_b64 vcc, -1, 0
	s_cmp_gt_i32 s42, 3
	v_cndmask_b32_e32 v95, v95, v96, vcc
	v_add_f32_e32 v96, v107, v95
	s_cselect_b64 vcc, -1, 0
	v_cndmask_b32_e32 v96, v95, v96, vcc
	v_pk_add_f32 v[22:23], v[22:23], v[96:97] op_sel_hi:[1,0]
	v_pk_add_f32 v[24:25], v[24:25], v[96:97] op_sel_hi:[1,0]
	v_pk_add_f32 v[26:27], v[26:27], v[96:97] op_sel_hi:[1,0]
	v_pk_add_f32 v[28:29], v[28:29], v[96:97] op_sel_hi:[1,0]
	v_pk_add_f32 v[30:31], v[30:31], v[96:97] op_sel_hi:[1,0]
	v_pk_add_f32 v[32:33], v[32:33], v[96:97] op_sel_hi:[1,0]
	v_pk_add_f32 v[34:35], v[34:35], v[96:97] op_sel_hi:[1,0]
	v_pk_add_f32 v[36:37], v[36:37], v[96:97] op_sel_hi:[1,0]

.LBB0_451:
	ds_read_b32 v0, v157 offset:4
	v_readlane_b32 s25, v244, 1
	s_mov_b32 s26, 0x4a670
	s_lshr_b32 s26, s26, s70
	s_and_b32 s26, s26, 1
	s_cmpk_eq_u32 s25, 0x200
	s_cselect_b32 s25, s26, 0
	v_readlane_b32 s18, v244, 44
	v_readlane_b32 s19, v244, 45
	s_waitcnt lgkmcnt(0)
	v_readfirstlane_b32 s20, v3
	v_readfirstlane_b32 s21, v2
	v_add_u32_e32 v0, 1, v0
	s_nop 1
	v_readfirstlane_b32 s22, v0
	ds_write_b32 v157, v0 offset:4
	global_atomic_add v4, v1, v158, s[18:19] sc0
	buffer_inv sc1
	s_mul_i32 s23, s22, s20
	s_waitcnt vmcnt(1)
	v_readfirstlane_b32 s3, v4
	s_add_i32 s3, s3, 1
	s_cmp_eq_u32 s3, s23
	s_cbranch_scc1 .Lxb_lead
	s_cmp_lg_u32 s25, 0
	s_cbranch_scc0 .Lxb_full
	global_atomic_add v1, v158, s[18:19] offset:128
	s_branch .LBB0_19
.Lxb_full:
	v_readlane_b32 s6, v244, 46
	v_readlane_b32 s7, v244, 47
	s_mov_b32 s3, 0
	s_waitcnt vmcnt(0)
	global_atomic_add v1, v158, s[18:19] offset:128
	s_nop 1

.Lxb_lead:
	buffer_wbl2 sc1
	v_readlane_b32 s6, v244, 48
	v_readlane_b32 s7, v244, 49
	s_sub_i32 s27, s23, s22
	s_mul_i32 s23, s22, s21
	s_mov_b32 s3, 0
	s_nop 1
	s_waitcnt vmcnt(0)
	global_atomic_add v1, v158, s[6:7]
	s_cmp_lg_u32 s25, 0
	s_cbranch_scc1 .Lxb_rel

.Lsw10b_x:
	s_mov_b64 exec, s[54:55]
	s_barrier
	s_add_i32 s7, s6, s7
	s_min_i32 s18, s7, 0x4000
	s_cmp_lt_i32 s6, s18
	s_cbranch_scc0 .LBB0_65
	s_load_dwordx2 s[28:29], s[0:1], 0x90
	s_load_dwordx2 s[26:27], s[0:1], 0x110
	s_ashr_i32 s7, s6, 31
	s_lshl_b64 s[20:21], s[6:7], 12
	v_and_b32_e32 v20, 63, v18
	s_waitcnt lgkmcnt(0)
	v_lshl_add_u64 v[66:67], s[28:29], 0, v[0:1]
	v_lshlrev_b32_e32 v0, 1, v19
	s_add_u32 s20, s28, s20
	v_lshl_add_u64 v[68:69], s[26:27], 0, v[0:1]
	v_lshlrev_b32_e32 v0, 4, v20
	s_addc_u32 s21, s29, s21
	v_lshl_add_u64 v[18:19], s[20:21], 0, v[0:1]
	s_mov_b64 s[20:21], 0x800
	v_lshl_add_u64 v[70:71], v[18:19], 0, s[20:21]
	s_lshl_b64 s[20:21], s[6:7], 11
	s_add_u32 s20, s26, s20
	v_lshlrev_b32_e32 v0, 3, v20
	s_addc_u32 s21, s27, s21
	v_lshl_add_u64 v[18:19], s[20:21], 0, v[0:1]
	s_mov_b64 s[20:21], 0x400
	v_lshl_add_u64 v[72:73], v[18:19], 0, s[20:21]
	s_branch .LBB0_533

.Lcv_p0a_s:
	s_mov_b32 s29, 2
	s_movk_i32 s89, 0x980
	s_branch .Lcv_go

.Lcv_p10:
	s_mov_b32 s28, 1
	s_mov_b32 s29, 1
	s_mov_b32 s26, s3
	s_cmpk_eq_u32 s71, 0x200
	s_cbranch_scc1 .LBB0_518
	s_mov_b32 s27, s71
	s_movk_i32 s89, 0x1a00
	s_branch .Lcv_go
.Lcv_s6a:
	s_mov_b32 s28, 0
	s_mov_b32 s29, 5
	s_add_i32 s26, s3, 0x260
	s_movk_i32 s27, 0x200
	s_movk_i32 s89, 0x1a00
	s_branch .Lcv_go
.Lcv_s6b:
	s_mov_b32 s28, 1
	s_mov_b32 s29, 3
	s_add_i32 s26, s3, 0x0
	s_movk_i32 s27, 0x200
	s_movk_i32 s89, 0x780
	s_branch .Lcv_go
.Lcv_s11:
	s_mov_b32 s28, 1
	s_mov_b32 s29, 3
	s_add_i32 s26, s3, 0x1e0
	s_movk_i32 s27, 0x200
	s_movk_i32 s89, 0x1a00
	s_branch .Lcv_go

.Lcv_done:
	s_cmp_eq_u32 s29, 0
	s_cbranch_scc1 .Lcv_p0b
	s_cmp_eq_u32 s29, 1
	s_cbranch_scc1 .LBB0_518
	s_cmp_eq_u32 s29, 5
	s_cbranch_scc1 .Lcv_s6b
	s_cmp_eq_u32 s29, 3
	s_cbranch_scc0 .LBB0_435
	s_waitcnt vmcnt(0) lgkmcnt(0)
	s_barrier
	s_branch .Lcvret_disp
	s_branch .LBB0_435
